# cooperative attention: 12-deep LDS->register tile read-ahead ring instead of 8
# speedup vs baseline: 1.0111x; 1.0089x over previous
; __device__ __forceinline__ void nat_phase(const Params& p, float* ldsf, int wave0, int nwaves) {
;     const int lane = threadIdx.x & 63, wid = __builtin_amdgcn_readfirstlane(threadIdx.x >> 6), l15 = lane & 15, lq = lane >> 4;
;     const u16* Qn = (const u16*)p.out; const u16* Kn = Qn + (size_t)NTOK * RW; const u16* VT = Kn + (size_t)NTOK * RW; const u16* Gn = VT + (size_t)NTOK * RW;
;     u16* MIX = (u16*)(p.ws + O_HN);
;     for (int item = wave0; item < 8192; item += nwaves) {
;         const int r = item & 255, h = (item >> 8) & 15, b = item >> 12;
;         const int rs = min(max(r - 4, 0), 248);
;         const u16* Qb = Qn + (size_t)(b * SEQ + r * 64) * RW + h * 64;
;         const u16* Kb = Kn + (size_t)(b * SEQ + rs * 64) * RW + h * 64;
;         const u16* Vb = VT + (size_t)((b * 16 + h) * 64) * SEQ + rs * 64;
;         float* tb = ldsf + wid * 256;
;         { const float* rpb = p.rpb + h * 465 + (rs - r + 7) * 31;
; #pragma unroll
;           for (int q = 0; q < 4; ++q) { const int e = lane + q * 64; if (e < 248) tb[e] = rpb[e]; } }
.LBB0_413:
	s_cmp_lt_i32 s58, 5
	s_cselect_b64 s[0:1], -1, 0
	s_cmp_gt_i32 s59, 4
	s_cselect_b64 s[4:5], -1, 0
	s_and_b64 s[0:1], s[0:1], s[4:5]
	s_andn2_b64 vcc, exec, s[0:1]
	s_cbranch_vccnz .LBB0_628
	v_readfirstlane_b32 s0, v254
	v_and_b32_e32 v96, 63, v254
	s_cmp_lt_u32 s0, 0
	v_and_b32_e32 v65, 15, v254
	s_cbranch_scc1 .LBB0_555
	s_setprio 0
	s_lshr_b32 s1, s0, 6
	s_mov_b32 s64, s56
	s_and_b32 s65, s57, 0xffff
	s_brev_b32 s66, -2
	s_mov_b32 s67, 0x27000
	s_mov_b32 s68, s54
	s_and_b32 s69, s55, 0xffff
	s_mov_b32 s70, s66
	s_mov_b32 s71, s67
	s_mov_b32 s72, s50
	s_and_b32 s73, s51, 0xffff
	s_movk_i32 s74, 0x7440
	s_mov_b32 s75, s67
	v_and_b32_e32 v237, 15, v254
	v_bfe_u32 v238, v254, 4, 2
	v_and_b32_e32 v242, 63, v254
	v_lshlrev_b32_e32 v243, 4, v238
	v_lshl_add_u32 v224, v237, 11, v243
	v_lshl_add_u32 v226, v237, 15, v243
	v_lshrrev_b32_e32 v244, 2, v237
	v_and_b32_e32 v245, 3, v237
	v_lshl_add_u32 v244, v244, 3, v245
	v_lshl_add_u32 v225, v244, 11, v243
	v_lshlrev_b32_e32 v243, 3, v238
	v_lshl_add_u32 v227, v237, 11, v243
	v_lshl_add_u32 v228, v237, 12, v243
	v_xor_b32_e32 v248, 16, v242
	v_lshlrev_b32_e32 v248, 2, v248
	v_xor_b32_e32 v249, 32, v242
	v_lshlrev_b32_e32 v249, 2, v249
	s_cmp_lt_u32 s1, 4
	s_cselect_b64 vcc, -1, 0
	s_nop 3
	v_cndmask_b32_e32 v50, v226, v225, vcc
	s_and_b32 s4, s1, 3
	s_lshl_b32 s4, s4, 8
	s_add_u32 s4, s4, 0x1e800
	v_lshl_add_u32 v244, v242, 2, s4
	v_mov_b32_e32 v243, 0xf2c9f2ca
	ds_write_b32 v244, v243
	v_mov_b32_e32 v252, 0x3e38aa3b
	v_mov_b32_e32 v253, 0x3e38aa3b
	s_mov_b32 s88, s2
	s_mov_b32 s94, s96
	s_cmpk_lg_u32 s96, 0x100
	s_cbranch_scc1 .Lmy_nat_unit
	s_and_b32 s88, s2, 7
	s_lshl_b32 s88, s88, 5
	s_lshr_b32 s4, s2, 3
	s_add_u32 s88, s88, s4
	s_movk_i32 s94, 0x100
	s_bfe_u32 s4, s2, 0x20003

; __device__ __forceinline__ void nat_phase(const Params& p, float* ldsf, int wave0, int nwaves) {
;     ...
;     for (int item = wave0; item < 8192; item += nwaves) {
;         const int r = item & 255, h = (item >> 8) & 15, b = item >> 12;
;         const int rs = min(max(r - 4, 0), 248);
;         const u16* Qb = Qn + (size_t)(b * SEQ + r * 64) * RW + h * 64;
;         const u16* Kb = Kn + (size_t)(b * SEQ + rs * 64) * RW + h * 64;
;         const u16* Vb = VT + (size_t)((b * 16 + h) * 64) * SEQ + rs * 64;
;         float* tb = ldsf + wid * 256;
;         { const float* rpb = p.rpb + h * 465 + (rs - r + 7) * 31;
; #pragma unroll
;           for (int q = 0; q < 4; ++q) { const int e = lane + q * 64; if (e < 248) tb[e] = rpb[e]; } }
; #pragma unroll 1
;         for (int qt = 0; qt < 4; ++qt) {
;             const int c0 = qt * 16, cs0 = (qt == 0) ? 0 : (qt == 1 ? 8 : (qt == 2 ? 24 : 32));
;             const int c = c0 + l15, csq = min(max(c - 8, 0), 48);
;             const bf16x8 bq0 = *(const bf16x8*)(Qb + (size_t)c * RW + lq * 8), bq1 = *(const bf16x8*)(Qb + (size_t)c * RW + 32 + lq * 8);
.Lmy_nat_nostag:
.Lmy_nat_unit:
	s_cmpk_gt_i32 s88, 0x3ff
	s_cbranch_scc1 .Lmy_nat_end
	s_lshr_b32 s4, s88, 5
	s_and_b32 s5, s4, 15
	s_lshr_b32 s6, s4, 4
	s_and_b32 s4, s88, 31
	s_lshl_b32 s4, s4, 3
	s_add_i32 s7, s4, -4
	s_max_i32 s7, s7, 0
	s_min_i32 s7, s7, 0xf1
	s_add_u32 s92, s4, s1
	s_add_i32 s90, s92, -4
	s_max_i32 s90, s90, 0
	s_min_i32 s90, s90, 0xf8
	s_sub_u32 s89, s90, s7
	s_lshl_b32 s8, s6, 14
	s_lshl_b32 s9, s92, 6
	s_add_u32 s9, s9, s8
	s_lshl_b32 s84, s5, 7
	s_lshl_b32 s76, s9, 11
	s_add_u32 s76, s76, s84
	s_add_u32 s79, s76, 0xc000000
	s_lshl_b32 s80, s9, 12
	s_add_u32 s80, s80, s84
	s_add_u32 s80, s80, 0x3800800
	s_lshl_b32 s85, s7, 6
	s_add_u32 s85, s85, s8
	s_lshl_b32 s77, s85, 11
	s_add_u32 s77, s77, s84
	s_add_u32 s77, s77, 0x4000000
	s_lshl_b32 s85, s6, 4
	s_add_u32 s85, s85, s5
	s_lshl_b32 s78, s85, 21
	s_lshl_b32 s86, s7, 7
	s_add_u32 s78, s78, s86
	s_add_u32 s78, s78, 0x8000000
	s_sub_i32 s3, s90, s92
	s_add_i32 s3, s3, 7
	s_mul_i32 s3, s3, 124
	s_add_u32 s3, s3, 0x1e000
	s_lshl_b32 s85, s89, 12
	v_and_b32_e32 v242, 63, v254
	v_lshl_add_u32 v48, v242, 4, s85
	s_add_u32 s85, s85, 0xf000
	v_lshl_add_u32 v49, v242, 4, s85
	s_barrier
	s_mul_i32 s85, s5, 1860
	s_lshl_b32 s86, s1, 8
	s_add_u32 s85, s85, s86
	v_lshlrev_b32_e32 v244, 2, v242
	buffer_load_dword v243, v244, s[72:75], s85 offen
	s_add_u32 s86, s86, 0x1e000
	v_add_u32_e32 v244, s86, v244
	s_waitcnt vmcnt(0)
	v_mul_f32_e32 v243, 0x41000000, v243
	ds_write_b32 v244, v243
	s_waitcnt lgkmcnt(0)
	s_mov_b32 s16, 0
.Lmy_nat_cqt:
	s_lshl_b32 s82, s16, 4
	s_add_i32 s83, s82, -8
	s_max_i32 s83, s83, 0
	s_min_i32 s83, s83, 32
	s_lshl_b32 s84, s82, 11
	s_add_u32 s84, s84, s76
	buffer_load_dwordx4 v[192:195], v224, s[68:71], s84 offen
	buffer_load_dwordx4 v[196:199], v224, s[68:71], s84 offen offset:64
	s_barrier
	s_cmp_lt_u32 s1, 4
	s_cbranch_scc0 .Lmy_nat_p1v
	s_cmp_eq_u32 s16, 0
	s_cbranch_scc0 .Lmy_nat_p1kw
	s_lshl_b32 s91, s83, 11
	s_add_u32 s91, s91, s77
	s_lshr_b32 s85, s1, 1
	s_lshl_b32 s85, s85, 13
	s_add_u32 s91, s91, s85
	s_and_b32 s85, s1, 1
	s_lshl_b32 s85, s85, 6
	s_add_u32 s91, s91, s85
	s_mov_b32 s93, 0x20000
	s_lshl_b32 s86, s1, 10
	s_mov_b32 m0, s86
	s_nop 0
	buffer_load_dwordx4 v50, s[68:71], s91 offen lds
	s_add_u32 m0, m0, 0x1000
	s_add_u32 s91, s91, s93
	buffer_load_dwordx4 v50, s[68:71], s91 offen lds
	s_add_u32 m0, m0, 0x1000
	s_add_u32 s91, s91, s93
	buffer_load_dwordx4 v50, s[68:71], s91 offen lds
	s_add_u32 m0, m0, 0x1000
	s_add_u32 s91, s91, s93
	buffer_load_dwordx4 v50, s[68:71], s91 offen lds
	s_add_u32 m0, m0, 0x1000
	s_add_u32 s91, s91, s93
	buffer_load_dwordx4 v50, s[68:71], s91 offen lds
	s_add_u32 m0, m0, 0x1000
	s_add_u32 s91, s91, s93
	buffer_load_dwordx4 v50, s[68:71], s91 offen lds
	s_add_u32 m0, m0, 0x1000
	s_add_u32 s91, s91, s93
	buffer_load_dwordx4 v50, s[68:71], s91 offen lds
	s_add_u32 m0, m0, 0x1000
	s_add_u32 s91, s91, s93
	buffer_load_dwordx4 v50, s[68:71], s91 offen lds
	s_add_u32 m0, m0, 0x1000
	s_add_u32 s91, s91, s93
	buffer_load_dwordx4 v50, s[68:71], s91 offen lds
	s_add_u32 m0, m0, 0x1000
	s_add_u32 s91, s91, s93
	buffer_load_dwordx4 v50, s[68:71], s91 offen lds
	s_add_u32 m0, m0, 0x1000
	s_add_u32 s91, s91, s93
	buffer_load_dwordx4 v50, s[68:71], s91 offen lds
	s_add_u32 m0, m0, 0x1000
	s_add_u32 s91, s91, s93
	buffer_load_dwordx4 v50, s[68:71], s91 offen lds
	s_add_u32 m0, m0, 0x1000
	s_add_u32 s91, s91, s93
	buffer_load_dwordx4 v50, s[68:71], s91 offen lds
	s_add_u32 m0, m0, 0x1000
	s_add_u32 s91, s91, s93
	buffer_load_dwordx4 v50, s[68:71], s91 offen lds
	s_add_u32 m0, m0, 0x1000
	s_add_u32 s91, s91, s93
	buffer_load_dwordx4 v50, s[68:71], s91 offen lds
	s_waitcnt vmcnt(0)
	s_branch .Lmy_nat_p1j

; __device__ __forceinline__ void nat_phase(const Params& p, float* ldsf, int wave0, int nwaves) {
;     ...
;         const u16* Vb = VT + (size_t)((b * 16 + h) * 64) * SEQ + rs * 64;
;     ...
;                 for (int mt = 0; mt < 4; ++mt) { const u16* vp = Vb + (size_t)(mt * 16 + l15) * SEQ + i * 64 + cs0 + lq * 8;
;                     o[mt] = __builtin_amdgcn_mfma_f32_16x16x32_bf16(*(const bf16x8*)vp, bp, o[mt], 0, 0, 0); }
.Lmy_nat_p1v:
	s_lshl_b32 s91, s83, 1
	s_add_u32 s91, s91, s78
	s_and_b32 s85, s1, 3
	s_lshl_b32 s85, s85, 19
	s_add_u32 s91, s91, s85
	s_movk_i32 s93, 0x80
	s_and_b32 s86, s1, 3
	s_lshl_b32 s86, s86, 10
	s_add_u32 s86, s86, 0xf000
	s_mov_b32 m0, s86
	s_nop 0
	buffer_load_dwordx4 v50, s[68:71], s91 offen lds
	s_add_u32 m0, m0, 0x1000
	s_add_u32 s91, s91, s93
	buffer_load_dwordx4 v50, s[68:71], s91 offen lds
	s_add_u32 m0, m0, 0x1000
	s_add_u32 s91, s91, s93
	buffer_load_dwordx4 v50, s[68:71], s91 offen lds
	s_add_u32 m0, m0, 0x1000
	s_add_u32 s91, s91, s93
	buffer_load_dwordx4 v50, s[68:71], s91 offen lds
	s_add_u32 m0, m0, 0x1000
	s_add_u32 s91, s91, s93
	buffer_load_dwordx4 v50, s[68:71], s91 offen lds
	s_add_u32 m0, m0, 0x1000
	s_add_u32 s91, s91, s93
	buffer_load_dwordx4 v50, s[68:71], s91 offen lds
	s_add_u32 m0, m0, 0x1000
	s_add_u32 s91, s91, s93
	buffer_load_dwordx4 v50, s[68:71], s91 offen lds
	s_add_u32 m0, m0, 0x1000
	s_add_u32 s91, s91, s93
	buffer_load_dwordx4 v50, s[68:71], s91 offen lds
	s_add_u32 m0, m0, 0x1000
	s_add_u32 s91, s91, s93
	buffer_load_dwordx4 v50, s[68:71], s91 offen lds
	s_add_u32 m0, m0, 0x1000
	s_add_u32 s91, s91, s93
	buffer_load_dwordx4 v50, s[68:71], s91 offen lds
	s_add_u32 m0, m0, 0x1000
	s_add_u32 s91, s91, s93
	buffer_load_dwordx4 v50, s[68:71], s91 offen lds
	s_add_u32 m0, m0, 0x1000
	s_add_u32 s91, s91, s93
	buffer_load_dwordx4 v50, s[68:71], s91 offen lds
	s_add_u32 m0, m0, 0x1000
	s_add_u32 s91, s91, s93
	buffer_load_dwordx4 v50, s[68:71], s91 offen lds
	s_add_u32 m0, m0, 0x1000
	s_add_u32 s91, s91, s93
	buffer_load_dwordx4 v50, s[68:71], s91 offen lds
	s_add_u32 m0, m0, 0x1000
	s_add_u32 s91, s91, s93
	buffer_load_dwordx4 v50, s[68:71], s91 offen lds

; __device__ __forceinline__ void nat_phase(const Params& p, float* ldsf, int wave0, int nwaves) {
;     ...
;             f32x4 sc[8][2];
; #pragma unroll
;             for (int i = 0; i < 8; ++i)
; #pragma unroll
;                 for (int hf = 0; hf < 2; ++hf) { const u16* kp = Kb + (size_t)(i * 64 + cs0 + (l15 >> 2) * 8 + hf * 4 + (l15 & 3)) * RW + lq * 8;
;                     const bf16x8 a0 = *(const bf16x8*)kp, a1 = *(const bf16x8*)(kp + 32); f32x4 z = {0.f, 0.f, 0.f, 0.f};
;                     z = __builtin_amdgcn_mfma_f32_16x16x32_bf16(a0, bq0, z, 0, 0, 0); z = __builtin_amdgcn_mfma_f32_16x16x32_bf16(a1, bq1, z, 0, 0, 0); sc[i][hf] = z; }
;             float mx = -1e30f;
; #pragma unroll
;             for (int i = 0; i < 8; ++i)
; #pragma unroll
;                 for (int hf = 0; hf < 2; ++hf)
; #pragma unroll
;                     for (int j = 0; j < 4; ++j) { const int kc = cs0 + lq * 8 + hf * 4 + j; const bool valid = (kc >= csq) && (kc < csq + 16); const int bc = valid ? (kc - c + 15) : 0;
;                         const float s = valid ? sc[i][hf][j] * 0.125f + tb[i * 31 + bc] : -1e30f; sc[i][hf][j] = s; mx = fmaxf(mx, s); }
;             mx = fmaxf(mx, __shfl_xor(mx, 16)); mx = fmaxf(mx, __shfl_xor(mx, 32));
.Lmy_nat_p2j:
	s_waitcnt lgkmcnt(0)
	ds_read_b128 v[0:3], v48 offset:0
	ds_read_b128 v[4:7], v48 offset:1024
	ds_read_b128 v[8:11], v48 offset:2048
	ds_read_b128 v[12:15], v48 offset:3072
	ds_read_b128 v[16:19], v48 offset:4096
	ds_read_b128 v[20:23], v48 offset:5120
	ds_read_b128 v[24:27], v48 offset:6144
	ds_read_b128 v[28:31], v48 offset:7168
	ds_read_b128 v[32:35], v48 offset:8192
	ds_read_b128 v[36:39], v48 offset:9216
	ds_read_b128 v[40:43], v48 offset:10240
	ds_read_b128 v[44:47], v48 offset:11264
	s_waitcnt lgkmcnt(11)
	v_mfma_f32_16x16x32_bf16 v[128:131], v[0:3], v[192:195], v[128:131]
	ds_read_b128 v[0:3], v48 offset:12288
	s_waitcnt lgkmcnt(11)
	v_mfma_f32_16x16x32_bf16 v[128:131], v[4:7], v[196:199], v[128:131]
	ds_read_b128 v[4:7], v48 offset:13312
	s_waitcnt lgkmcnt(11)
	v_mfma_f32_16x16x32_bf16 v[132:135], v[8:11], v[192:195], v[132:135]
	ds_read_b128 v[8:11], v48 offset:14336
	s_waitcnt lgkmcnt(11)
	v_mfma_f32_16x16x32_bf16 v[132:135], v[12:15], v[196:199], v[132:135]
	ds_read_b128 v[12:15], v48 offset:15360
	s_waitcnt lgkmcnt(11)
	v_mfma_f32_16x16x32_bf16 v[136:139], v[16:19], v[192:195], v[136:139]
	ds_read_b128 v[16:19], v48 offset:16384
	s_waitcnt lgkmcnt(11)
	v_mfma_f32_16x16x32_bf16 v[136:139], v[20:23], v[196:199], v[136:139]
	ds_read_b128 v[20:23], v48 offset:17408
	s_waitcnt lgkmcnt(11)
	v_mfma_f32_16x16x32_bf16 v[140:143], v[24:27], v[192:195], v[140:143]
	ds_read_b128 v[24:27], v48 offset:18432
	s_waitcnt lgkmcnt(11)
	v_mfma_f32_16x16x32_bf16 v[140:143], v[28:31], v[196:199], v[140:143]
	ds_read_b128 v[28:31], v48 offset:19456
	s_waitcnt lgkmcnt(11)
	v_mfma_f32_16x16x32_bf16 v[144:147], v[32:35], v[192:195], v[144:147]
	ds_read_b128 v[32:35], v48 offset:20480
	s_waitcnt lgkmcnt(11)
	v_mfma_f32_16x16x32_bf16 v[144:147], v[36:39], v[196:199], v[144:147]
	ds_read_b128 v[36:39], v48 offset:21504
	s_waitcnt lgkmcnt(11)
	v_mfma_f32_16x16x32_bf16 v[148:151], v[40:43], v[192:195], v[148:151]
	ds_read_b128 v[40:43], v48 offset:22528
	s_waitcnt lgkmcnt(11)
	v_mfma_f32_16x16x32_bf16 v[148:151], v[44:47], v[196:199], v[148:151]
	ds_read_b128 v[44:47], v48 offset:23552
	s_waitcnt lgkmcnt(11)
	v_mfma_f32_16x16x32_bf16 v[152:155], v[0:3], v[192:195], v[152:155]
	ds_read_b128 v[0:3], v48 offset:24576
	s_waitcnt lgkmcnt(11)
	v_mfma_f32_16x16x32_bf16 v[152:155], v[4:7], v[196:199], v[152:155]
	ds_read_b128 v[4:7], v48 offset:25600
	s_waitcnt lgkmcnt(11)
	v_mfma_f32_16x16x32_bf16 v[156:159], v[8:11], v[192:195], v[156:159]
	ds_read_b128 v[8:11], v48 offset:26624
	s_waitcnt lgkmcnt(11)
	v_mfma_f32_16x16x32_bf16 v[156:159], v[12:15], v[196:199], v[156:159]
	ds_read_b128 v[12:15], v48 offset:27648
	s_waitcnt lgkmcnt(11)
	v_mfma_f32_16x16x32_bf16 v[160:163], v[16:19], v[192:195], v[160:163]
	ds_read_b128 v[16:19], v48 offset:28672
	s_waitcnt lgkmcnt(11)
	v_mfma_f32_16x16x32_bf16 v[160:163], v[20:23], v[196:199], v[160:163]
	ds_read_b128 v[20:23], v48 offset:29696
	s_waitcnt lgkmcnt(11)
	v_mfma_f32_16x16x32_bf16 v[164:167], v[24:27], v[192:195], v[164:167]
	ds_read_b128 v[24:27], v48 offset:30720
	s_waitcnt lgkmcnt(11)
	v_mfma_f32_16x16x32_bf16 v[164:167], v[28:31], v[196:199], v[164:167]
	ds_read_b128 v[28:31], v48 offset:31744
	s_waitcnt lgkmcnt(11)
	v_mfma_f32_16x16x32_bf16 v[168:171], v[32:35], v[192:195], v[168:171]
	s_waitcnt lgkmcnt(10)
	v_mfma_f32_16x16x32_bf16 v[168:171], v[36:39], v[196:199], v[168:171]
	s_waitcnt lgkmcnt(9)
	v_mfma_f32_16x16x32_bf16 v[172:175], v[40:43], v[192:195], v[172:175]
	s_waitcnt lgkmcnt(8)
	v_mfma_f32_16x16x32_bf16 v[172:175], v[44:47], v[196:199], v[172:175]
	s_waitcnt lgkmcnt(7)
	v_mfma_f32_16x16x32_bf16 v[176:179], v[0:3], v[192:195], v[176:179]
	s_waitcnt lgkmcnt(6)
	v_mfma_f32_16x16x32_bf16 v[176:179], v[4:7], v[196:199], v[176:179]
	s_waitcnt lgkmcnt(5)
	v_mfma_f32_16x16x32_bf16 v[180:183], v[8:11], v[192:195], v[180:183]
	s_waitcnt lgkmcnt(4)
	v_mfma_f32_16x16x32_bf16 v[180:183], v[12:15], v[196:199], v[180:183]
	s_waitcnt lgkmcnt(3)
	v_mfma_f32_16x16x32_bf16 v[184:187], v[16:19], v[192:195], v[184:187]
	s_waitcnt lgkmcnt(2)
	v_mfma_f32_16x16x32_bf16 v[184:187], v[20:23], v[196:199], v[184:187]
	s_waitcnt lgkmcnt(1)
	v_mfma_f32_16x16x32_bf16 v[188:191], v[24:27], v[192:195], v[188:191]
	s_waitcnt lgkmcnt(0)
	v_mfma_f32_16x16x32_bf16 v[188:191], v[28:31], v[196:199], v[188:191]
	s_lshl_b32 s84, s82, 11
	s_add_u32 s84, s84, s79
	buffer_load_dwordx2 v[216:217], v227, s[68:71], s84 offen offset:0
	buffer_load_dwordx2 v[218:219], v227, s[68:71], s84 offen offset:32
	buffer_load_dwordx2 v[220:221], v227, s[68:71], s84 offen offset:64
	buffer_load_dwordx2 v[222:223], v227, s[68:71], s84 offen offset:96
	v_max3_f32 v239, v128, v129, v130
	v_max3_f32 v239, v239, v131, v132
	v_max3_f32 v239, v239, v133, v134
	v_max3_f32 v239, v239, v135, v136
	v_max3_f32 v239, v239, v137, v138
	v_max3_f32 v239, v239, v139, v140
	v_max3_f32 v239, v239, v141, v142
	v_max3_f32 v239, v239, v143, v144
	v_max3_f32 v239, v239, v145, v146
	v_max3_f32 v239, v239, v147, v148
	v_max3_f32 v239, v239, v149, v150
	v_max3_f32 v239, v239, v151, v152
	v_max3_f32 v239, v239, v153, v154
	v_max3_f32 v239, v239, v155, v156
	v_max3_f32 v239, v239, v157, v158
	v_max3_f32 v239, v239, v159, v160
	v_max3_f32 v239, v239, v161, v162
	v_max3_f32 v239, v239, v163, v164
	v_max3_f32 v239, v239, v165, v166
	v_max3_f32 v239, v239, v167, v168
	v_max3_f32 v239, v239, v169, v170
	v_max3_f32 v239, v239, v171, v172
	v_max3_f32 v239, v239, v173, v174
	v_max3_f32 v239, v239, v175, v176
	v_max3_f32 v239, v239, v177, v178
	v_max3_f32 v239, v239, v179, v180
	v_max3_f32 v239, v239, v181, v182
	v_max3_f32 v239, v239, v183, v184
	v_max3_f32 v239, v239, v185, v186
	v_max3_f32 v239, v239, v187, v188
	v_max3_f32 v239, v239, v189, v190
	v_max_f32_e32 v239, v239, v191
	ds_bpermute_b32 v242, v248, v239
	s_waitcnt lgkmcnt(0)
; __device__ __forceinline__ void nat_phase(const Params& p, float* ldsf, int wave0, int nwaves) {
;     ...
;             mx = fmaxf(mx, __shfl_xor(mx, 16)); mx = fmaxf(mx, __shfl_xor(mx, 32));
;             float sum = 0.f;
; #pragma unroll
;             for (int i = 0; i < 8; ++i)
; #pragma unroll
;                 for (int hf = 0; hf < 2; ++hf)
; #pragma unroll
;                     for (int j = 0; j < 4; ++j) { const float e = __expf(sc[i][hf][j] - mx); sc[i][hf][j] = e; sum += e; }
;             sum += __shfl_xor(sum, 16); sum += __shfl_xor(sum, 32);
;             const float inv = 1.0f / sum;
	v_max_f32_e32 v239, v239, v242
	ds_bpermute_b32 v242, v249, v239
	s_waitcnt lgkmcnt(0)
	v_max_f32_e32 v239, v239, v242
	v_mul_f32_e64 v242, -v239, v252
	v_mov_b32_e32 v243, v242
	v_pk_fma_f32 v[128:129], v[128:129], v[252:253], v[242:243]
	v_pk_fma_f32 v[130:131], v[130:131], v[252:253], v[242:243]
	v_pk_fma_f32 v[132:133], v[132:133], v[252:253], v[242:243]
	v_pk_fma_f32 v[134:135], v[134:135], v[252:253], v[242:243]
	v_pk_fma_f32 v[136:137], v[136:137], v[252:253], v[242:243]
	v_pk_fma_f32 v[138:139], v[138:139], v[252:253], v[242:243]
	v_pk_fma_f32 v[140:141], v[140:141], v[252:253], v[242:243]
	v_pk_fma_f32 v[142:143], v[142:143], v[252:253], v[242:243]
	v_pk_fma_f32 v[144:145], v[144:145], v[252:253], v[242:243]
	v_pk_fma_f32 v[146:147], v[146:147], v[252:253], v[242:243]
	v_pk_fma_f32 v[148:149], v[148:149], v[252:253], v[242:243]
	v_pk_fma_f32 v[150:151], v[150:151], v[252:253], v[242:243]
	v_pk_fma_f32 v[152:153], v[152:153], v[252:253], v[242:243]
	v_pk_fma_f32 v[154:155], v[154:155], v[252:253], v[242:243]
	v_pk_fma_f32 v[156:157], v[156:157], v[252:253], v[242:243]
	v_pk_fma_f32 v[158:159], v[158:159], v[252:253], v[242:243]
	v_pk_fma_f32 v[160:161], v[160:161], v[252:253], v[242:243]
	v_pk_fma_f32 v[162:163], v[162:163], v[252:253], v[242:243]
	v_pk_fma_f32 v[164:165], v[164:165], v[252:253], v[242:243]
	v_pk_fma_f32 v[166:167], v[166:167], v[252:253], v[242:243]
	v_pk_fma_f32 v[168:169], v[168:169], v[252:253], v[242:243]
	v_pk_fma_f32 v[170:171], v[170:171], v[252:253], v[242:243]
	v_pk_fma_f32 v[172:173], v[172:173], v[252:253], v[242:243]
	v_pk_fma_f32 v[174:175], v[174:175], v[252:253], v[242:243]
	v_pk_fma_f32 v[176:177], v[176:177], v[252:253], v[242:243]
	v_pk_fma_f32 v[178:179], v[178:179], v[252:253], v[242:243]
	v_pk_fma_f32 v[180:181], v[180:181], v[252:253], v[242:243]
	v_pk_fma_f32 v[182:183], v[182:183], v[252:253], v[242:243]
	v_pk_fma_f32 v[184:185], v[184:185], v[252:253], v[242:243]
	v_pk_fma_f32 v[186:187], v[186:187], v[252:253], v[242:243]
	v_pk_fma_f32 v[188:189], v[188:189], v[252:253], v[242:243]
	v_pk_fma_f32 v[190:191], v[190:191], v[252:253], v[242:243]
	v_exp_f32_e32 v128, v128
	v_exp_f32_e32 v129, v129
	v_exp_f32_e32 v130, v130
	v_exp_f32_e32 v131, v131
	v_exp_f32_e32 v132, v132
	v_exp_f32_e32 v133, v133
	v_exp_f32_e32 v134, v134
	v_exp_f32_e32 v135, v135
	v_exp_f32_e32 v136, v136
	v_exp_f32_e32 v137, v137
	v_exp_f32_e32 v138, v138
	v_exp_f32_e32 v139, v139
	v_exp_f32_e32 v140, v140
	v_exp_f32_e32 v141, v141
	v_exp_f32_e32 v142, v142
	v_exp_f32_e32 v143, v143
	v_exp_f32_e32 v144, v144
	v_exp_f32_e32 v145, v145
	v_exp_f32_e32 v146, v146
	v_exp_f32_e32 v147, v147
	v_exp_f32_e32 v148, v148
	v_exp_f32_e32 v149, v149
	v_exp_f32_e32 v150, v150
	v_exp_f32_e32 v151, v151
	v_exp_f32_e32 v152, v152
	v_exp_f32_e32 v153, v153
	v_exp_f32_e32 v154, v154
	v_exp_f32_e32 v155, v155
	v_exp_f32_e32 v156, v156
	v_exp_f32_e32 v157, v157
	v_exp_f32_e32 v158, v158
	v_exp_f32_e32 v159, v159
	v_exp_f32_e32 v160, v160
	v_exp_f32_e32 v161, v161
	v_exp_f32_e32 v162, v162
	v_exp_f32_e32 v163, v163
	v_exp_f32_e32 v164, v164
	v_exp_f32_e32 v165, v165
	v_exp_f32_e32 v166, v166
	v_exp_f32_e32 v167, v167
	v_exp_f32_e32 v168, v168
	v_exp_f32_e32 v169, v169
	v_exp_f32_e32 v170, v170
	v_exp_f32_e32 v171, v171
	v_exp_f32_e32 v172, v172
	v_exp_f32_e32 v173, v173
	v_exp_f32_e32 v174, v174
	v_exp_f32_e32 v175, v175
	v_exp_f32_e32 v176, v176
	v_exp_f32_e32 v177, v177
	v_exp_f32_e32 v178, v178
	v_exp_f32_e32 v179, v179
	v_exp_f32_e32 v180, v180
	v_exp_f32_e32 v181, v181
	v_exp_f32_e32 v182, v182
	v_exp_f32_e32 v183, v183
	v_exp_f32_e32 v184, v184
	v_exp_f32_e32 v185, v185
	v_exp_f32_e32 v186, v186
	v_exp_f32_e32 v187, v187
	v_exp_f32_e32 v188, v188
	v_exp_f32_e32 v189, v189
	v_exp_f32_e32 v190, v190
	v_exp_f32_e32 v191, v191
	s_nop 0
	v_pk_add_f32 v[244:245], v[128:129], v[130:131]
	v_pk_add_f32 v[246:247], v[132:133], v[134:135]
	v_pk_add_f32 v[244:245], v[244:245], v[136:137]
	v_pk_add_f32 v[246:247], v[246:247], v[138:139]
	v_pk_add_f32 v[244:245], v[244:245], v[140:141]
	v_pk_add_f32 v[246:247], v[246:247], v[142:143]
	v_pk_add_f32 v[244:245], v[244:245], v[144:145]
	v_pk_add_f32 v[246:247], v[246:247], v[146:147]
	v_pk_add_f32 v[244:245], v[244:245], v[148:149]
	v_pk_add_f32 v[246:247], v[246:247], v[150:151]
	v_pk_add_f32 v[244:245], v[244:245], v[152:153]
	v_pk_add_f32 v[246:247], v[246:247], v[154:155]
	v_pk_add_f32 v[244:245], v[244:245], v[156:157]
	v_pk_add_f32 v[246:247], v[246:247], v[158:159]
	v_pk_add_f32 v[244:245], v[244:245], v[160:161]
	v_pk_add_f32 v[246:247], v[246:247], v[162:163]
	v_pk_add_f32 v[244:245], v[244:245], v[164:165]
	v_pk_add_f32 v[246:247], v[246:247], v[166:167]
	v_pk_add_f32 v[244:245], v[244:245], v[168:169]
	v_pk_add_f32 v[246:247], v[246:247], v[170:171]
	v_pk_add_f32 v[244:245], v[244:245], v[172:173]
	v_pk_add_f32 v[246:247], v[246:247], v[174:175]
	v_pk_add_f32 v[244:245], v[244:245], v[176:177]
	v_pk_add_f32 v[246:247], v[246:247], v[178:179]
	v_pk_add_f32 v[244:245], v[244:245], v[180:181]
	v_pk_add_f32 v[246:247], v[246:247], v[182:183]
	v_pk_add_f32 v[244:245], v[244:245], v[184:185]
	v_pk_add_f32 v[246:247], v[246:247], v[186:187]
	v_pk_add_f32 v[244:245], v[244:245], v[188:189]
	v_pk_add_f32 v[246:247], v[246:247], v[190:191]
	v_pk_add_f32 v[244:245], v[244:245], v[246:247]
	v_add_f32_e32 v240, v244, v245
	ds_bpermute_b32 v242, v248, v240
	s_waitcnt lgkmcnt(0)
	v_add_f32_e32 v240, v240, v242
	ds_bpermute_b32 v242, v249, v240
	s_waitcnt lgkmcnt(0)
; __device__ __forceinline__ unsigned cvt_pk_bf16(float lo, float hi) { unsigned r; asm volatile("v_cvt_pk_bf16_f32 %0, %1, %2" : "=v"(r) : "v"(lo), "v"(hi)); return r; }
; __device__ __forceinline__ void nat_phase(const Params& p, float* ldsf, int wave0, int nwaves) {
;     ...
;             const float inv = 1.0f / sum;
;             f32x4 o[4];
; #pragma unroll
;             for (int mt = 0; mt < 4; ++mt) o[mt] = (f32x4){0.f, 0.f, 0.f, 0.f};
; #pragma unroll
;             for (int i = 0; i < 8; ++i) {
;                 u32x4 pw; pw.x = cvt_pk_bf16(sc[i][0][0] * inv, sc[i][0][1] * inv); pw.y = cvt_pk_bf16(sc[i][0][2] * inv, sc[i][0][3] * inv);
;                 pw.z = cvt_pk_bf16(sc[i][1][0] * inv, sc[i][1][1] * inv); pw.w = cvt_pk_bf16(sc[i][1][2] * inv, sc[i][1][3] * inv);
;                 const bf16x8 bp = __builtin_bit_cast(bf16x8, pw);
	v_add_f32_e32 v240, v240, v242
	v_rcp_f32_e32 v242, v240
	s_nop 0
	v_mov_b32_e32 v243, v242
	v_pk_mul_f32 v[128:129], v[128:129], v[242:243]
	v_pk_mul_f32 v[130:131], v[130:131], v[242:243]
	v_pk_mul_f32 v[132:133], v[132:133], v[242:243]
	v_pk_mul_f32 v[134:135], v[134:135], v[242:243]
	v_pk_mul_f32 v[136:137], v[136:137], v[242:243]
	v_pk_mul_f32 v[138:139], v[138:139], v[242:243]
	v_pk_mul_f32 v[140:141], v[140:141], v[242:243]
	v_pk_mul_f32 v[142:143], v[142:143], v[242:243]
	v_pk_mul_f32 v[144:145], v[144:145], v[242:243]
	v_pk_mul_f32 v[146:147], v[146:147], v[242:243]
	v_pk_mul_f32 v[148:149], v[148:149], v[242:243]
	v_pk_mul_f32 v[150:151], v[150:151], v[242:243]
	v_pk_mul_f32 v[152:153], v[152:153], v[242:243]
	v_pk_mul_f32 v[154:155], v[154:155], v[242:243]
	v_pk_mul_f32 v[156:157], v[156:157], v[242:243]
	v_pk_mul_f32 v[158:159], v[158:159], v[242:243]
	v_pk_mul_f32 v[160:161], v[160:161], v[242:243]
	v_pk_mul_f32 v[162:163], v[162:163], v[242:243]
	v_pk_mul_f32 v[164:165], v[164:165], v[242:243]
	v_pk_mul_f32 v[166:167], v[166:167], v[242:243]
	v_pk_mul_f32 v[168:169], v[168:169], v[242:243]
	v_pk_mul_f32 v[170:171], v[170:171], v[242:243]
	v_pk_mul_f32 v[172:173], v[172:173], v[242:243]
	v_pk_mul_f32 v[174:175], v[174:175], v[242:243]
	v_pk_mul_f32 v[176:177], v[176:177], v[242:243]
	v_pk_mul_f32 v[178:179], v[178:179], v[242:243]
	v_pk_mul_f32 v[180:181], v[180:181], v[242:243]
	v_pk_mul_f32 v[182:183], v[182:183], v[242:243]
	v_pk_mul_f32 v[184:185], v[184:185], v[242:243]
	v_pk_mul_f32 v[186:187], v[186:187], v[242:243]
	v_pk_mul_f32 v[188:189], v[188:189], v[242:243]
	v_pk_mul_f32 v[190:191], v[190:191], v[242:243]
	v_cvt_pk_bf16_f32 v128, v128, v129
	v_cvt_pk_bf16_f32 v129, v130, v131
	v_cvt_pk_bf16_f32 v130, v132, v133
	v_cvt_pk_bf16_f32 v131, v134, v135
	v_cvt_pk_bf16_f32 v136, v136, v137
	v_cvt_pk_bf16_f32 v137, v138, v139
	v_cvt_pk_bf16_f32 v138, v140, v141
	v_cvt_pk_bf16_f32 v139, v142, v143
	v_cvt_pk_bf16_f32 v144, v144, v145
	v_cvt_pk_bf16_f32 v145, v146, v147
	v_cvt_pk_bf16_f32 v146, v148, v149
	v_cvt_pk_bf16_f32 v147, v150, v151
	v_cvt_pk_bf16_f32 v152, v152, v153
	v_cvt_pk_bf16_f32 v153, v154, v155
	v_cvt_pk_bf16_f32 v154, v156, v157
	v_cvt_pk_bf16_f32 v155, v158, v159
	v_cvt_pk_bf16_f32 v160, v160, v161
	v_cvt_pk_bf16_f32 v161, v162, v163
	v_cvt_pk_bf16_f32 v162, v164, v165
	v_cvt_pk_bf16_f32 v163, v166, v167
	v_cvt_pk_bf16_f32 v168, v168, v169
	v_cvt_pk_bf16_f32 v169, v170, v171
	v_cvt_pk_bf16_f32 v170, v172, v173
	v_cvt_pk_bf16_f32 v171, v174, v175
	v_cvt_pk_bf16_f32 v176, v176, v177
	v_cvt_pk_bf16_f32 v177, v178, v179
	v_cvt_pk_bf16_f32 v178, v180, v181
	v_cvt_pk_bf16_f32 v179, v182, v183
	v_cvt_pk_bf16_f32 v184, v184, v185
	v_cvt_pk_bf16_f32 v185, v186, v187
	v_cvt_pk_bf16_f32 v186, v188, v189
	v_cvt_pk_bf16_f32 v187, v190, v191
	s_cmp_lt_u32 s1, 4
	s_cbranch_scc1 .Lmy_nat_p3j
	s_waitcnt vmcnt(4)
.Lmy_nat_p3j:
	s_barrier
	s_cmp_lt_u32 s1, 4
	s_cbranch_scc0 .Lmy_nat_p4j
	s_cmp_lt_u32 s16, 3
	s_cbranch_scc0 .Lmy_nat_p4j
	s_add_i32 s87, s82, 8
	s_min_i32 s87, s87, 32
	s_lshl_b32 s91, s87, 11
	s_add_u32 s91, s91, s77
	s_lshr_b32 s85, s1, 1
	s_lshl_b32 s85, s85, 13
	s_add_u32 s91, s91, s85
	s_and_b32 s85, s1, 1
	s_lshl_b32 s85, s85, 6
	s_add_u32 s91, s91, s85
	s_mov_b32 s93, 0x20000
	s_lshl_b32 s86, s1, 10
	s_mov_b32 m0, s86
	s_nop 0
	buffer_load_dwordx4 v50, s[68:71], s91 offen lds
	s_add_u32 m0, m0, 0x1000
	s_add_u32 s91, s91, s93
	buffer_load_dwordx4 v50, s[68:71], s91 offen lds
	s_add_u32 m0, m0, 0x1000
	s_add_u32 s91, s91, s93
	buffer_load_dwordx4 v50, s[68:71], s91 offen lds
	s_add_u32 m0, m0, 0x1000
	s_add_u32 s91, s91, s93
	buffer_load_dwordx4 v50, s[68:71], s91 offen lds
	s_add_u32 m0, m0, 0x1000
	s_add_u32 s91, s91, s93
	buffer_load_dwordx4 v50, s[68:71], s91 offen lds
	s_add_u32 m0, m0, 0x1000
	s_add_u32 s91, s91, s93
	buffer_load_dwordx4 v50, s[68:71], s91 offen lds
	s_add_u32 m0, m0, 0x1000
	s_add_u32 s91, s91, s93
	buffer_load_dwordx4 v50, s[68:71], s91 offen lds
	s_add_u32 m0, m0, 0x1000
	s_add_u32 s91, s91, s93
	buffer_load_dwordx4 v50, s[68:71], s91 offen lds
	s_add_u32 m0, m0, 0x1000
	s_add_u32 s91, s91, s93
	buffer_load_dwordx4 v50, s[68:71], s91 offen lds
	s_add_u32 m0, m0, 0x1000
	s_add_u32 s91, s91, s93
	buffer_load_dwordx4 v50, s[68:71], s91 offen lds
	s_add_u32 m0, m0, 0x1000
	s_add_u32 s91, s91, s93
	buffer_load_dwordx4 v50, s[68:71], s91 offen lds
	s_add_u32 m0, m0, 0x1000
	s_add_u32 s91, s91, s93
	buffer_load_dwordx4 v50, s[68:71], s91 offen lds
	s_add_u32 m0, m0, 0x1000
	s_add_u32 s91, s91, s93
	buffer_load_dwordx4 v50, s[68:71], s91 offen lds
	s_add_u32 m0, m0, 0x1000
	s_add_u32 s91, s91, s93
	buffer_load_dwordx4 v50, s[68:71], s91 offen lds
	s_add_u32 m0, m0, 0x1000
	s_add_u32 s91, s91, s93
	buffer_load_dwordx4 v50, s[68:71], s91 offen lds
; __device__ __forceinline__ unsigned cvt_pk_bf16(float lo, float hi) { unsigned r; asm volatile("v_cvt_pk_bf16_f32 %0, %1, %2" : "=v"(r) : "v"(lo), "v"(hi)); return r; }
; __device__ __forceinline__ void nat_phase(const Params& p, float* ldsf, int wave0, int nwaves) {
;     ...
; #pragma unroll
;             for (int i = 0; i < 8; ++i) {
;                 u32x4 pw; pw.x = cvt_pk_bf16(sc[i][0][0] * inv, sc[i][0][1] * inv); pw.y = cvt_pk_bf16(sc[i][0][2] * inv, sc[i][0][3] * inv);
;                 pw.z = cvt_pk_bf16(sc[i][1][0] * inv, sc[i][1][1] * inv); pw.w = cvt_pk_bf16(sc[i][1][2] * inv, sc[i][1][3] * inv);
;                 const bf16x8 bp = __builtin_bit_cast(bf16x8, pw);
; #pragma unroll
;                 for (int mt = 0; mt < 4; ++mt) { const u16* vp = Vb + (size_t)(mt * 16 + l15) * SEQ + i * 64 + cs0 + lq * 8;
;                     o[mt] = __builtin_amdgcn_mfma_f32_16x16x32_bf16(*(const bf16x8*)vp, bp, o[mt], 0, 0, 0); }
;             }
.Lmy_nat_p4j:
	ds_read_b128 v[0:3], v49 offset:0
	ds_read_b128 v[4:7], v49 offset:1024
	ds_read_b128 v[8:11], v49 offset:2048
	ds_read_b128 v[12:15], v49 offset:3072
	ds_read_b128 v[16:19], v49 offset:4096
	ds_read_b128 v[20:23], v49 offset:5120
	ds_read_b128 v[24:27], v49 offset:6144
	ds_read_b128 v[28:31], v49 offset:7168
	ds_read_b128 v[32:35], v49 offset:8192
	ds_read_b128 v[36:39], v49 offset:9216
	ds_read_b128 v[40:43], v49 offset:10240
	ds_read_b128 v[44:47], v49 offset:11264
	s_waitcnt lgkmcnt(11)
	v_mfma_f32_16x16x32_bf16 v[200:203], v[0:3], v[128:131], 0
	ds_read_b128 v[0:3], v49 offset:12288
	s_waitcnt lgkmcnt(11)
	v_mfma_f32_16x16x32_bf16 v[204:207], v[4:7], v[128:131], 0
	ds_read_b128 v[4:7], v49 offset:13312
	s_waitcnt lgkmcnt(11)
	v_mfma_f32_16x16x32_bf16 v[208:211], v[8:11], v[128:131], 0
	ds_read_b128 v[8:11], v49 offset:14336
	s_waitcnt lgkmcnt(11)
	v_mfma_f32_16x16x32_bf16 v[212:215], v[12:15], v[128:131], 0
	ds_read_b128 v[12:15], v49 offset:15360
	s_waitcnt lgkmcnt(11)
	v_mfma_f32_16x16x32_bf16 v[200:203], v[16:19], v[136:139], v[200:203]
	ds_read_b128 v[16:19], v49 offset:16384
	s_waitcnt lgkmcnt(11)
	v_mfma_f32_16x16x32_bf16 v[204:207], v[20:23], v[136:139], v[204:207]
	ds_read_b128 v[20:23], v49 offset:17408
	s_waitcnt lgkmcnt(11)
	v_mfma_f32_16x16x32_bf16 v[208:211], v[24:27], v[136:139], v[208:211]
	ds_read_b128 v[24:27], v49 offset:18432
	s_waitcnt lgkmcnt(11)
	v_mfma_f32_16x16x32_bf16 v[212:215], v[28:31], v[136:139], v[212:215]
	ds_read_b128 v[28:31], v49 offset:19456
	s_waitcnt lgkmcnt(11)
	v_mfma_f32_16x16x32_bf16 v[200:203], v[32:35], v[144:147], v[200:203]
	ds_read_b128 v[32:35], v49 offset:20480
	s_waitcnt lgkmcnt(11)
	v_mfma_f32_16x16x32_bf16 v[204:207], v[36:39], v[144:147], v[204:207]
	ds_read_b128 v[36:39], v49 offset:21504
	s_waitcnt lgkmcnt(11)
	v_mfma_f32_16x16x32_bf16 v[208:211], v[40:43], v[144:147], v[208:211]
	ds_read_b128 v[40:43], v49 offset:22528
	s_waitcnt lgkmcnt(11)
	v_mfma_f32_16x16x32_bf16 v[212:215], v[44:47], v[144:147], v[212:215]
	ds_read_b128 v[44:47], v49 offset:23552
	s_waitcnt lgkmcnt(11)
	v_mfma_f32_16x16x32_bf16 v[200:203], v[0:3], v[152:155], v[200:203]
	ds_read_b128 v[0:3], v49 offset:24576
	s_waitcnt lgkmcnt(11)
	v_mfma_f32_16x16x32_bf16 v[204:207], v[4:7], v[152:155], v[204:207]
	ds_read_b128 v[4:7], v49 offset:25600
	s_waitcnt lgkmcnt(11)
	v_mfma_f32_16x16x32_bf16 v[208:211], v[8:11], v[152:155], v[208:211]
	ds_read_b128 v[8:11], v49 offset:26624
	s_waitcnt lgkmcnt(11)
	v_mfma_f32_16x16x32_bf16 v[212:215], v[12:15], v[152:155], v[212:215]
	ds_read_b128 v[12:15], v49 offset:27648
	s_waitcnt lgkmcnt(11)
	v_mfma_f32_16x16x32_bf16 v[200:203], v[16:19], v[160:163], v[200:203]
	ds_read_b128 v[16:19], v49 offset:28672
	s_waitcnt lgkmcnt(11)
	v_mfma_f32_16x16x32_bf16 v[204:207], v[20:23], v[160:163], v[204:207]
	ds_read_b128 v[20:23], v49 offset:29696
	s_waitcnt lgkmcnt(11)
	v_mfma_f32_16x16x32_bf16 v[208:211], v[24:27], v[160:163], v[208:211]
	ds_read_b128 v[24:27], v49 offset:30720
	s_waitcnt lgkmcnt(11)
	v_mfma_f32_16x16x32_bf16 v[212:215], v[28:31], v[160:163], v[212:215]
	ds_read_b128 v[28:31], v49 offset:31744
	s_waitcnt lgkmcnt(11)
	v_mfma_f32_16x16x32_bf16 v[200:203], v[32:35], v[168:171], v[200:203]
	s_waitcnt lgkmcnt(10)
	v_mfma_f32_16x16x32_bf16 v[204:207], v[36:39], v[168:171], v[204:207]
	s_waitcnt lgkmcnt(9)
	v_mfma_f32_16x16x32_bf16 v[208:211], v[40:43], v[168:171], v[208:211]
	s_waitcnt lgkmcnt(8)
	v_mfma_f32_16x16x32_bf16 v[212:215], v[44:47], v[168:171], v[212:215]
	s_waitcnt lgkmcnt(7)
	v_mfma_f32_16x16x32_bf16 v[200:203], v[0:3], v[176:179], v[200:203]
	s_waitcnt lgkmcnt(6)
	v_mfma_f32_16x16x32_bf16 v[204:207], v[4:7], v[176:179], v[204:207]
	s_waitcnt lgkmcnt(5)
	v_mfma_f32_16x16x32_bf16 v[208:211], v[8:11], v[176:179], v[208:211]
	s_waitcnt lgkmcnt(4)
	v_mfma_f32_16x16x32_bf16 v[212:215], v[12:15], v[176:179], v[212:215]
	s_waitcnt lgkmcnt(3)
	v_mfma_f32_16x16x32_bf16 v[200:203], v[16:19], v[184:187], v[200:203]
	s_waitcnt lgkmcnt(2)
	v_mfma_f32_16x16x32_bf16 v[204:207], v[20:23], v[184:187], v[204:207]
	s_waitcnt lgkmcnt(1)
	v_mfma_f32_16x16x32_bf16 v[208:211], v[24:27], v[184:187], v[208:211]
	s_waitcnt lgkmcnt(0)
	v_mfma_f32_16x16x32_bf16 v[212:215], v[28:31], v[184:187], v[212:215]
	s_cmp_lt_u32 s1, 4
	s_cbranch_scc0 .Lmy_nat_p5z
	s_cmp_lt_u32 s16, 3
	s_cbranch_scc0 .Lmy_nat_p5z
	s_waitcnt vmcnt(15)
	s_branch .Lmy_nat_p5j
